# rope tiles of the row epilogue: cos/sin table rows touched once up front so the per-row table loads hit in L1
# baseline (speedup 1.0000x reference)
.LBB0_435:
	s_or_b64 exec, exec, s[50:51]
	s_cmp_lg_u32 s62, s3
	s_cbranch_scc1 .Lrope_nopf
	v_lshlrev_b64 v[206:207], 6, v[178:179]
	v_lshl_add_u64 v[208:209], v[162:163], 0, v[206:207]
	v_lshl_add_u64 v[210:211], v[164:165], 0, v[206:207]
	global_load_dword v212, v[208:209], off
	global_load_dword v213, v[210:211], off
	global_load_dword v212, v[208:209], off offset:1024
	global_load_dword v213, v[210:211], off offset:1024
	global_load_dword v212, v[208:209], off offset:2048
	global_load_dword v213, v[210:211], off offset:2048
	global_load_dword v212, v[208:209], off offset:3072
	global_load_dword v213, v[210:211], off offset:3072
	v_add_co_u32_e32 v208, vcc, 0x2000, v208
	s_nop 1
	v_addc_co_u32_e32 v209, vcc, 0, v209, vcc
	v_add_co_u32_e32 v210, vcc, 0x2000, v210
	s_nop 1
	v_addc_co_u32_e32 v211, vcc, 0, v211, vcc
	global_load_dword v212, v[208:209], off
	global_load_dword v213, v[210:211], off
	global_load_dword v212, v[208:209], off offset:1024
	global_load_dword v213, v[210:211], off offset:1024
	global_load_dword v212, v[208:209], off offset:2048
	global_load_dword v213, v[210:211], off offset:2048
	global_load_dword v212, v[208:209], off offset:3072
	global_load_dword v213, v[210:211], off offset:3072
.Lrope_nopf:
	v_and_b32_e32 v143, 64, v222
	v_xor_b32_e32 v142, 16, v222
	v_add_u32_e32 v148, 64, v143
	v_cmp_lt_i32_e32 vcc, v142, v148
	v_pk_add_f32 v[132:133], v[180:181], v[132:133]
	v_pk_add_f32 v[128:129], v[184:185], v[128:129]
	v_cndmask_b32_e32 v142, v222, v142, vcc
	v_lshlrev_b32_e32 v206, 2, v142
	v_mov_b32_e32 v142, v128
	v_mov_b32_e32 v143, v132
	v_mov_b32_e32 v132, v129
	v_pk_add_f32 v[128:129], v[142:143], v[132:133]
	ds_bpermute_b32 v133, v206, v129
	ds_bpermute_b32 v132, v206, v128
	v_xor_b32_e32 v142, 32, v222
	v_cmp_lt_i32_e32 vcc, v142, v148
	s_cmp_ge_i32 s62, s17
	s_cselect_b64 s[54:55], -1, 0
	v_cndmask_b32_e32 v142, v222, v142, vcc
	v_lshlrev_b32_e32 v180, 2, v142
	s_waitcnt lgkmcnt(0)
	v_pk_add_f32 v[128:129], v[128:129], v[132:133]
	ds_bpermute_b32 v133, v180, v129
	ds_bpermute_b32 v132, v180, v128
	s_cmp_lt_i32 s62, s17
	s_waitcnt lgkmcnt(0)
	v_pk_add_f32 v[128:129], v[128:129], v[132:133]
	s_nop 0
	v_pk_fma_f32 v[152:153], s[18:19], v[128:129], v[198:199] op_sel_hi:[1,1,0]
	v_pk_add_f32 v[132:133], v[186:187], v[134:135]
	v_mul_f32_e32 v128, 0x4b800000, v153
	v_cmp_gt_f32_e32 vcc, s39, v153
	v_mov_b32_e32 v134, v132
	v_cmp_gt_f32_e64 s[50:51], s39, v152
	v_cndmask_b32_e32 v128, v153, v128, vcc
	v_rsq_f32_e32 v142, v128
	v_pk_add_f32 v[128:129], v[182:183], v[138:139]
	v_pk_add_f32 v[138:139], v[192:193], v[146:147]
	v_mov_b32_e32 v135, v128
	v_mov_b32_e32 v128, v133
	v_pk_add_f32 v[132:133], v[134:135], v[128:129]
	ds_bpermute_b32 v135, v206, v133
	ds_bpermute_b32 v134, v206, v132
	v_mul_f32_e32 v128, 0x45800000, v142
	v_cndmask_b32_e32 v128, v142, v128, vcc
	v_pk_mul_f32 v[146:147], v[124:125], v[128:129] op_sel_hi:[1,0]
	v_pk_mul_f32 v[122:123], v[122:123], v[128:129] op_sel_hi:[1,0]
	s_waitcnt lgkmcnt(0)
	v_pk_add_f32 v[142:143], v[132:133], v[134:135]
	v_pk_add_f32 v[132:133], v[136:137], v[144:145]
	v_pk_add_f32 v[134:135], v[188:189], v[140:141]
	v_mov_b32_e32 v137, v132
	v_mov_b32_e32 v136, v134
	v_mov_b32_e32 v132, v135
	v_pk_add_f32 v[132:133], v[136:137], v[132:133]
	v_pk_add_f32 v[136:137], v[190:191], v[150:151]
	v_mov_b32_e32 v140, v138
	v_mov_b32_e32 v141, v136
	v_mov_b32_e32 v136, v139
	v_pk_add_f32 v[140:141], v[140:141], v[136:137]
	ds_bpermute_b32 v135, v206, v133
	ds_bpermute_b32 v134, v206, v132
	ds_bpermute_b32 v145, v206, v141
	ds_bpermute_b32 v144, v206, v140
	ds_bpermute_b32 v149, v180, v143
	ds_bpermute_b32 v148, v180, v142
	s_waitcnt lgkmcnt(0)
	v_pk_add_f32 v[136:137], v[132:133], v[134:135]
	ds_bpermute_b32 v139, v180, v137
	v_pk_add_f32 v[132:133], v[140:141], v[144:145]
	ds_bpermute_b32 v138, v180, v136
	ds_bpermute_b32 v135, v180, v133
	ds_bpermute_b32 v134, v180, v132
	v_pk_mul_f32 v[144:145], v[126:127], v[128:129] op_sel_hi:[1,0]
	v_pk_mul_f32 v[140:141], v[120:121], v[128:129] op_sel_hi:[1,0]
	s_cbranch_scc1 .LBB0_437
	v_and_b32_e32 v121, 0x7fffffff, v147
	v_and_b32_e32 v120, 0x7fffffff, v146
	v_pk_fma_f32 v[120:121], v[120:121], s[98:99], 1.0 op_sel_hi:[1,0,0]
	v_mov_b64_e32 v[124:125], s[10:11]
	v_rcp_f32_e32 v120, v120
	v_rcp_f32_e32 v121, v121
	v_pk_mul_f32 v[150:151], v[146:147], v[146:147]
	v_and_b32_e32 v183, 0x7fffffff, v145
	v_and_b32_e32 v182, 0x7fffffff, v144
	v_pk_fma_f32 v[126:127], v[120:121], s[38:39], v[124:125] op_sel_hi:[1,0,0]
	v_pk_mul_f32 v[150:151], v[150:151], s[16:17] op_sel_hi:[1,0]
	v_pk_fma_f32 v[182:183], v[182:183], s[98:99], 1.0 op_sel_hi:[1,0,0]
	v_pk_fma_f32 v[126:127], v[120:121], v[126:127], s[58:59] op_sel_hi:[1,1,0]
	v_exp_f32_e32 v150, v150
	v_exp_f32_e32 v151, v151
	v_rcp_f32_e32 v182, v182
	v_rcp_f32_e32 v183, v183
	v_pk_fma_f32 v[126:127], v[120:121], v[126:127], s[90:91] op_sel_hi:[1,1,0]
	v_pk_mul_f32 v[184:185], v[144:145], v[144:145]
	v_pk_fma_f32 v[126:127], v[120:121], v[126:127], s[0:1] op_sel_hi:[1,1,0]
	v_and_b32_e32 v187, 0x7fffffff, v141
	v_pk_mul_f32 v[120:121], v[120:121], v[126:127]
	v_and_b32_e32 v186, 0x7fffffff, v140
	v_pk_mul_f32 v[120:121], v[150:151], v[120:121]
	v_pk_fma_f32 v[150:151], v[182:183], s[38:39], v[124:125] op_sel_hi:[1,0,0]
	v_pk_mul_f32 v[184:185], v[184:185], s[16:17] op_sel_hi:[1,0]
	v_pk_fma_f32 v[186:187], v[186:187], s[98:99], 1.0 op_sel_hi:[1,0,0]
	v_pk_fma_f32 v[150:151], v[182:183], v[150:151], s[58:59] op_sel_hi:[1,1,0]
	v_exp_f32_e32 v184, v184
	v_exp_f32_e32 v185, v185
	v_rcp_f32_e32 v186, v186
	v_rcp_f32_e32 v187, v187
	v_pk_fma_f32 v[150:151], v[182:183], v[150:151], s[90:91] op_sel_hi:[1,1,0]
	v_pk_mul_f32 v[188:189], v[140:141], v[140:141]
	v_pk_fma_f32 v[150:151], v[182:183], v[150:151], s[0:1] op_sel_hi:[1,1,0]
	v_pk_mul_f32 v[188:189], v[188:189], s[16:17] op_sel_hi:[1,0]
	v_pk_mul_f32 v[150:151], v[182:183], v[150:151]
	v_and_b32_e32 v191, 0x7fffffff, v123
	v_pk_mul_f32 v[150:151], v[184:185], v[150:151]
	v_pk_fma_f32 v[184:185], v[186:187], s[38:39], v[124:125] op_sel_hi:[1,0,0]
	v_and_b32_e32 v190, 0x7fffffff, v122
	v_pk_fma_f32 v[184:185], v[186:187], v[184:185], s[58:59] op_sel_hi:[1,1,0]
	v_exp_f32_e32 v188, v188
	v_exp_f32_e32 v189, v189
	v_pk_fma_f32 v[190:191], v[190:191], s[98:99], 1.0 op_sel_hi:[1,0,0]
	v_pk_fma_f32 v[184:185], v[186:187], v[184:185], s[90:91] op_sel_hi:[1,1,0]
	v_rcp_f32_e32 v190, v190
	v_rcp_f32_e32 v191, v191
	v_pk_fma_f32 v[184:185], v[186:187], v[184:185], s[0:1] op_sel_hi:[1,1,0]
	v_pk_mul_f32 v[126:127], v[146:147], v[120:121]
	v_pk_mul_f32 v[184:185], v[186:187], v[184:185]
	v_pk_fma_f32 v[124:125], v[190:191], s[38:39], v[124:125] op_sel_hi:[1,0,0]
	v_pk_mul_f32 v[184:185], v[188:189], v[184:185]
	v_pk_mul_f32 v[188:189], v[122:123], v[122:123]
	v_pk_fma_f32 v[120:121], v[146:147], v[120:121], v[146:147] neg_lo:[1,0,0] neg_hi:[1,0,0]
	v_pk_mul_f32 v[188:189], v[188:189], s[16:17] op_sel_hi:[1,0]
	v_cmp_gt_f32_e32 vcc, 0, v146
	v_pk_fma_f32 v[124:125], v[190:191], v[124:125], s[58:59] op_sel_hi:[1,1,0]
	v_exp_f32_e32 v188, v188
	v_exp_f32_e32 v189, v189
	v_cndmask_b32_e32 v146, v120, v126, vcc
	v_cmp_gt_f32_e32 vcc, 0, v147
	v_pk_mul_f32 v[182:183], v[144:145], v[150:151]
	v_pk_fma_f32 v[124:125], v[190:191], v[124:125], s[90:91] op_sel_hi:[1,1,0]
	v_pk_fma_f32 v[150:151], v[144:145], v[150:151], v[144:145] neg_lo:[1,0,0] neg_hi:[1,0,0]
	v_cndmask_b32_e32 v147, v121, v127, vcc
	v_cmp_gt_f32_e32 vcc, 0, v144
	v_pk_fma_f32 v[124:125], v[190:191], v[124:125], s[0:1] op_sel_hi:[1,1,0]
	v_pk_mul_f32 v[186:187], v[140:141], v[184:185]
	v_cndmask_b32_e32 v144, v150, v182, vcc
	v_cmp_gt_f32_e32 vcc, 0, v145
	v_pk_mul_f32 v[124:125], v[190:191], v[124:125]
	v_pk_fma_f32 v[184:185], v[140:141], v[184:185], v[140:141] neg_lo:[1,0,0] neg_hi:[1,0,0]
	v_cndmask_b32_e32 v145, v151, v183, vcc
	v_cmp_gt_f32_e32 vcc, 0, v140
	v_pk_mul_f32 v[124:125], v[188:189], v[124:125]
	s_nop 0
	v_cndmask_b32_e32 v140, v184, v186, vcc
	v_cmp_gt_f32_e32 vcc, 0, v141
	v_pk_mul_f32 v[188:189], v[122:123], v[124:125]
	v_pk_fma_f32 v[124:125], v[122:123], v[124:125], v[122:123] neg_lo:[1,0,0] neg_hi:[1,0,0]
	v_cndmask_b32_e32 v141, v185, v187, vcc
	v_cmp_gt_f32_e32 vcc, 0, v122
	s_nop 1
	v_cndmask_b32_e32 v122, v124, v188, vcc
	v_cmp_gt_f32_e32 vcc, 0, v123
	s_nop 1
	v_cndmask_b32_e32 v123, v125, v189, vcc
